# P3: residual rows of epilogue row groups 1-3 prefetched from inside the K-loop (iteration 24 of -2..28)
# speedup vs baseline: 1.0031x; 1.0031x over previous
;     __device__ __forceinline__ void operator()(const f32x4 (&acc)[2][2][4][2], const Unit& u, int wr, int wc, int fr, int fq) const {
;     ...
;         for (int g = 0; g < 8; ++g) { if constexpr (HAS_RS2) r2[g] = __hip_atomic_load(rs2 + row0 + (g >> 2) * HALF + (g & 3) * 16, __ATOMIC_RELAXED, __HIP_MEMORY_SCOPE_AGENT); else if constexpr (HAS_NRM) r2[g] = ssq[NRM_OFF + rown + (g >> 2) * HALF + (g & 3) * 16]; else r2[g] = 0.f; }
;         u32x2 raw[8][2][2];
;         if constexpr (BASEB) {
; #pragma unroll
;             for (int g = 0; g < 4; ++g)
; #pragma unroll
;                 for (int bj = 0; bj < 2; ++bj)
; #pragma unroll
;                     for (int n = 0; n < 2; ++n) raw[g][bj][n] = *(const u32x2*)((const bf16_t*)base + (size_t)(row0 + (g >> 2) * HALF + (g & 3) * 16) * 2048 + col0 + bj * HALF + n * 16);
.LBB0_651:
	s_cmp_eq_u32 s46, 24
	s_cbranch_scc0 .Lp3pf_skip
	v_lshl_add_u32 v230, s24, 8, v1
	v_lshl_or_b32 v232, s22, 8, v196
	v_ashrrev_i32_e32 v233, 31, v232
	v_lshlrev_b64 v[232:233], 1, v[232:233]
	v_ashrrev_i32_e32 v231, 31, v230
	v_lshlrev_b64 v[230:231], 12, v[230:231]
	v_lshl_add_u64 v[232:233], s[90:91], 0, v[232:233]
	v_lshl_add_u64 v[230:231], v[232:233], 0, v[230:231]
	s_mov_b64 s[40:41], 0x10000
	v_lshl_add_u64 v[232:233], v[230:231], 0, s[40:41]
	global_load_dwordx2 v[234:235], v[232:233], off
	global_load_dwordx2 v[236:237], v[232:233], off offset:32
	global_load_dwordx2 v[238:239], v[232:233], off offset:256
	global_load_dwordx2 v[240:241], v[232:233], off offset:288
	s_mov_b64 s[40:41], 0x20000
	v_lshl_add_u64 v[232:233], v[230:231], 0, s[40:41]
	global_load_dwordx2 v[244:245], v[232:233], off
	global_load_dwordx2 v[246:247], v[232:233], off offset:32
	global_load_dwordx2 v[248:249], v[232:233], off offset:256
	global_load_dwordx2 v[250:251], v[232:233], off offset:288
	s_mov_b64 s[40:41], 0x30000
	v_lshl_add_u64 v[232:233], v[230:231], 0, s[40:41]
	global_load_dwordx2 v[252:253], v[232:233], off
	global_load_dwordx2 v[254:255], v[232:233], off offset:32
	global_load_dwordx2 v[230:231], v[232:233], off offset:256
	s_nop 0
	global_load_dwordx2 v[232:233], v[232:233], off offset:288

;     __device__ __forceinline__ void operator()(const f32x4 (&acc)[2][2][4][2], const Unit& u, int wr, int wc, int fr, int fq) const {
;         const int row0 = u.pm * BM + wr * 64 + fr, col0 = u.pn * BM + wc * 32 + 4 * fq;
;         float r2[8];
;         int rown = row0; asm volatile("" : "+v"(rown));
; #pragma unroll
;         for (int g = 0; g < 8; ++g) { if constexpr (HAS_RS2) r2[g] = __hip_atomic_load(rs2 + row0 + (g >> 2) * HALF + (g & 3) * 16, __ATOMIC_RELAXED, __HIP_MEMORY_SCOPE_AGENT); else if constexpr (HAS_NRM) r2[g] = ssq[NRM_OFF + rown + (g >> 2) * HALF + (g & 3) * 16]; else r2[g] = 0.f; }
;         u32x2 raw[8][2][2];
;         if constexpr (BASEB) {
; #pragma unroll
;             for (int g = 0; g < 4; ++g)
; #pragma unroll
;                 for (int bj = 0; bj < 2; ++bj)
; #pragma unroll
;                     for (int n = 0; n < 2; ++n) raw[g][bj][n] = *(const u32x2*)((const bf16_t*)base + (size_t)(row0 + (g >> 2) * HALF + (g & 3) * 16) * 2048 + col0 + bj * HALF + n * 16);
;         }
;         f32x4 nx[2][2], ny[2][2]; if constexpr (!BASEB) { ldbase(nx, (size_t)row0 * 2048 + col0); ldbase(ny, (size_t)(row0 + 16) * 2048 + col0); }
; #pragma unroll
;         for (int g = 0; g < 8; ++g) { if constexpr (HAS_RS2) r2[g] = __builtin_amdgcn_rcpf(r2[g] * (1.0f / 2048.0f) + 1e-5f); else if constexpr (HAS_NRM) r2[g] = __builtin_amdgcn_sqrtf(r2[g] * (1.0f / 2048.0f) + 1e-5f);     else r2[g] = 1.f; }
; #pragma unroll
;         for (int g = 0; g < 8; ++g) {
;             const int ai = g >> 2, m = g & 3;
;             const int row = row0 + ai * HALF + m * 16; const size_t off = (size_t)row * 2048 + col0; float s = 0.f;
;             f32x4 bs[2][2];
;             if constexpr (BASEB) {
;                 if (g < 4) {
; #pragma unroll
;                     for (int bj = 0; bj < 2; ++bj)
; #pragma unroll
;                         for (int n = 0; n < 2; ++n) raw[g + 4][bj][n] = *(const u32x2*)((const bf16_t*)base + (size_t)(row0 + ((g + 4) >> 2) * HALF + ((g + 4) & 3) * 16) * 2048 + col0 + bj * HALF + n * 16);
;                 }
; #pragma unroll
;                 for (int bj = 0; bj < 2; ++bj)
; #pragma unroll
;                     for (int n = 0; n < 2; ++n) bs[bj][n] = bf4_to_f32(raw[g][bj][n]);
;             } else {
; #pragma unroll
;             for (int bj = 0; bj < 2; ++bj)
; #pragma unroll
.LBB0_654:
	v_lshl_add_u32 v182, s24, 8, v1
	v_lshl_or_b32 v140, s22, 8, v196
	v_mov_b32_e32 v142, v182
	v_ashrrev_i32_e32 v141, 31, v140
	v_lshlrev_b64 v[156:157], 1, v[140:141]
	v_ashrrev_i32_e32 v183, 31, v182
	v_ashrrev_i32_e32 v143, 31, v142
	v_lshl_add_u64 v[148:149], s[90:91], 0, v[156:157]
	v_lshlrev_b64 v[210:211], 12, v[182:183]
	v_lshl_add_u64 v[142:143], v[142:143], 2, s[6:7]
	v_lshl_add_u64 v[144:145], v[148:149], 0, v[210:211]
	v_add_co_u32_e32 v216, vcc, 0x20000, v142
	global_load_dwordx2 v[212:213], v[144:145], off
	global_load_dwordx2 v[214:215], v[144:145], off offset:32
	global_load_dwordx2 v[218:219], v[144:145], off offset:256
	v_addc_co_u32_e32 v217, vcc, 0, v143, vcc
	global_load_dwordx2 v[220:221], v[144:145], off offset:288
	global_load_dword v209, v[216:217], off
	v_or_b32_e32 v172, 16, v182
	v_or_b32_e32 v160, 32, v182
	v_or_b32_e32 v146, 48, v182
	v_add_u32_e32 v142, 0x80, v182
	v_ashrrev_i32_e32 v173, 31, v172
	v_ashrrev_i32_e32 v161, 31, v160
	v_ashrrev_i32_e32 v147, 31, v146
	v_ashrrev_i32_e32 v143, 31, v142
	v_lshlrev_b64 v[184:185], 12, v[172:173]
	v_lshlrev_b64 v[170:171], 12, v[160:161]
	v_lshlrev_b64 v[158:159], 12, v[146:147]
	v_lshlrev_b64 v[144:145], 12, v[142:143]
	v_lshl_add_u64 v[150:151], v[148:149], 0, v[184:185]
	v_lshl_add_u64 v[152:153], v[148:149], 0, v[170:171]
	v_lshl_add_u64 v[148:149], v[148:149], 0, v[158:159]
	v_lshl_add_u64 v[154:155], s[90:91], 0, v[144:145]
	v_mov_b64_e32 v[192:193], v[234:235]
	v_mov_b64_e32 v[190:191], v[236:237]
	v_mov_b64_e32 v[188:189], v[238:239]
	v_mov_b64_e32 v[186:187], v[240:241]
	v_mov_b64_e32 v[180:181], v[244:245]
	v_mov_b64_e32 v[178:179], v[246:247]
	v_mov_b64_e32 v[176:177], v[248:249]
	v_mov_b64_e32 v[174:175], v[250:251]
	v_mov_b64_e32 v[168:169], v[252:253]
	v_mov_b64_e32 v[166:167], v[254:255]
	v_mov_b64_e32 v[164:165], v[230:231]
	v_mov_b64_e32 v[162:163], v[232:233]
	v_lshl_add_u64 v[148:149], v[154:155], 0, v[156:157]
	global_load_dwordx2 v[154:155], v[148:149], off
	global_load_dwordx2 v[152:153], v[148:149], off offset:32
	global_load_dwordx2 v[150:151], v[148:149], off offset:256
	s_nop 0
	global_load_dwordx2 v[148:149], v[148:149], off offset:288
	s_nop 0
	global_load_dword v208, v[216:217], off offset:64
	global_load_dword v207, v[216:217], off offset:128
	global_load_dword v206, v[216:217], off offset:192
	global_load_dword v205, v[216:217], off offset:512
	global_load_dword v204, v[216:217], off offset:576
	global_load_dword v203, v[216:217], off offset:640
	global_load_dword v202, v[216:217], off offset:704
	v_lshl_add_u64 v[210:211], s[70:71], 0, v[210:211]
	v_lshl_add_u64 v[210:211], v[210:211], 0, v[156:157]
	s_waitcnt vmcnt(0)
	v_lshlrev_b32_e32 v216, 16, v212
	v_and_b32_e32 v217, 0xffff0000, v212
	v_lshlrev_b32_e32 v212, 16, v213
	v_and_b32_e32 v213, 0xffff0000, v213
	v_lshlrev_b32_e32 v222, 16, v214
	v_fmamk_f32 v209, v209, 0x3a000000, v200
	v_sqrt_f32_e32 v228, v209
	v_and_b32_e32 v223, 0xffff0000, v214
	v_lshlrev_b32_e32 v214, 16, v215
	v_and_b32_e32 v215, 0xffff0000, v215
	v_pk_fma_f32 v[128:129], v[228:229], v[212:213], v[128:129] op_sel_hi:[0,1,1]
	v_pk_fma_f32 v[126:127], v[228:229], v[216:217], v[126:127] op_sel_hi:[0,1,1]
	v_pk_fma_f32 v[124:125], v[228:229], v[214:215], v[124:125] op_sel_hi:[0,1,1]
	v_pk_fma_f32 v[122:123], v[228:229], v[222:223], v[122:123] op_sel_hi:[0,1,1]
	v_mul_f32_e32 v214, v129, v129
	v_mul_f32_e32 v209, v127, v127
	v_cvt_pk_bf16_f32 v212, v126, v127
	v_cvt_pk_bf16_f32 v213, v128, v129
	v_mul_f32_e32 v127, v123, v123
	v_fmac_f32_e32 v214, v128, v128
	v_mul_f32_e32 v128, v125, v125
	v_lshlrev_b32_e32 v224, 16, v218
	v_and_b32_e32 v225, 0xffff0000, v218
	v_lshlrev_b32_e32 v218, 16, v219
	v_and_b32_e32 v219, 0xffff0000, v219
	v_fmac_f32_e32 v209, v126, v126
	v_fmac_f32_e32 v127, v122, v122
	v_fmac_f32_e32 v128, v124, v124
	v_lshlrev_b32_e32 v226, 16, v220
	v_and_b32_e32 v227, 0xffff0000, v220
	v_lshlrev_b32_e32 v220, 16, v221
	v_and_b32_e32 v221, 0xffff0000, v221
	v_add_f32_e32 v126, v209, v214
	v_add_f32_e32 v127, v127, v128
	v_pk_fma_f32 v[120:121], v[228:229], v[218:219], v[120:121] op_sel_hi:[0,1,1]
	v_pk_fma_f32 v[118:119], v[228:229], v[224:225], v[118:119] op_sel_hi:[0,1,1]
	global_store_dwordx2 v[210:211], v[212:213], off
	v_add_f32_e32 v126, v126, v127
	v_cvt_pk_bf16_f32 v122, v122, v123
	v_mul_f32_e32 v123, v119, v119
	v_mul_f32_e32 v127, v121, v121
	v_pk_fma_f32 v[116:117], v[228:229], v[220:221], v[116:117] op_sel_hi:[0,1,1]
	v_pk_fma_f32 v[128:129], v[228:229], v[226:227], v[114:115] op_sel_hi:[0,1,1]
	v_fmac_f32_e32 v123, v118, v118
	v_fmac_f32_e32 v127, v120, v120
	v_mul_f32_e32 v114, v129, v129
	v_mul_f32_e32 v115, v117, v117
	v_add_f32_e32 v123, v123, v127
	v_fmac_f32_e32 v114, v128, v128
	v_fmac_f32_e32 v115, v116, v116
	v_add_f32_e32 v123, v126, v123
	v_add_f32_e32 v114, v114, v115
	v_add_f32_e32 v114, v123, v114
	v_and_b32_e32 v123, 64, v201
	v_xor_b32_e32 v115, 16, v201
	v_add_u32_e32 v127, 64, v123
	v_cmp_lt_i32_e32 vcc, v115, v127
	v_cvt_pk_bf16_f32 v123, v124, v125
	global_store_dwordx2 v[210:211], v[122:123], off offset:32
	v_cvt_pk_bf16_f32 v118, v118, v119
	v_cvt_pk_bf16_f32 v119, v120, v121
	global_store_dwordx2 v[210:211], v[118:119], off offset:256
	v_cndmask_b32_e32 v115, v201, v115, vcc
	v_lshlrev_b32_e32 v126, 2, v115
	v_mov_b32_e32 v115, v114
	s_nop 1
	v_permlane16_swap_b32_e32 v115, v114
	v_cvt_pk_bf16_f32 v118, v128, v129
	v_cvt_pk_bf16_f32 v119, v116, v117
	global_store_dwordx2 v[210:211], v[118:119], off offset:288
	s_waitcnt lgkmcnt(0)
	v_add_f32_e32 v114, v114, v115
	v_xor_b32_e32 v115, 32, v201
	v_cmp_lt_i32_e32 vcc, v115, v127
	s_nop 1
	v_cndmask_b32_e32 v115, v201, v115, vcc
	v_lshlrev_b32_e32 v127, 2, v115
	v_mov_b32_e32 v115, v114
	s_nop 1
	v_permlane32_swap_b32_e32 v115, v114
	s_and_saveexec_b64 s[22:23], s[4:5]
	s_cbranch_execz .LBB0_656
	v_lshl_add_u64 v[116:117], v[182:183], 2, s[6:7]
	s_waitcnt lgkmcnt(0)
	v_add_f32_e32 v114, v114, v115
	global_atomic_add_f32 v[116:117], v114, off
